# grid barrier release: all workgroups poll the cross-XCD release word directly
# baseline (speedup 1.0000x reference)
; __device__ __forceinline__ unsigned xb_ld(unsigned* p)              { return __hip_atomic_load(p, __ATOMIC_RELAXED, __HIP_MEMORY_SCOPE_AGENT); }
; __device__ __forceinline__ unsigned xb_add(unsigned* p, unsigned v) { return __hip_atomic_fetch_add(p, v, __ATOMIC_RELAXED, __HIP_MEMORY_SCOPE_AGENT); }
; #define XB_SPIN(cond, bar) do { unsigned _sp = 0; while (cond) { __builtin_amdgcn_s_sleep(1); \
;     if ((++_sp & 255u) == 0u) { if (xb_ld(&(bar)[XB_TMO])) break; if (_sp > XB_SPIN_CAP) { atomicAdd(&(bar)[XB_TMO], 1u); break; } } } } while (0)
; __device__ __forceinline__ void xcd_barrier(const XcdBarrier& b) {
;     ...
;         const unsigned old = xb_add(&bar[XB_XSUB(b.x)], 1u);
;         const unsigned gen = old / nloc;
;         if (old + 1u == (gen + 1u) * nloc) {
;             __builtin_amdgcn_fence(__ATOMIC_RELEASE, "agent");
;             asm volatile("s_waitcnt vmcnt(0)" ::: "memory");
;             const unsigned og = xb_add(&bar[XB_TOP], 1u);
;             const unsigned tg = og / nx;
;             if (og + 1u == (tg + 1u) * nx) xb_add(&bar[XB_TOPGEN], 1u);
;             else XB_SPIN(xb_ld(&bar[XB_TOPGEN]) == tg, bar);
;             __builtin_amdgcn_fence(__ATOMIC_ACQUIRE, "agent");
;             xb_add(&bar[XB_XGEN(b.x)], 1u);
;             asm volatile("s_waitcnt vmcnt(0)" ::: "memory");
;         } else {
;             XB_SPIN(xb_ld(&bar[XB_XGEN(b.x)]) == gen, bar);
;             __builtin_amdgcn_fence(__ATOMIC_ACQUIRE, "agent");
;             asm volatile("s_waitcnt vmcnt(0)" ::: "memory");
;         }
.LBB0_1567:
	s_or_b64 exec, exec, s[6:7]
	v_cvt_f32_u32_e32 v5, v3
	s_waitcnt vmcnt(0)
	v_readfirstlane_b32 s4, v4
	v_sub_u32_e32 v4, 0, v3
	v_rcp_iflag_f32_e32 v5, v5
	v_add_u32_e32 v6, s4, v0
	v_mul_f32_e32 v5, 0x4f7ffffe, v5
	v_cvt_u32_f32_e32 v5, v5
	v_mul_lo_u32 v0, v4, v5
	v_mul_hi_u32 v0, v5, v0
	v_add_u32_e32 v0, v5, v0
	v_mul_hi_u32 v0, v6, v0
	v_mul_lo_u32 v4, v0, v3
	v_sub_u32_e32 v4, v6, v4
	v_add_u32_e32 v5, 1, v0
	v_cmp_ge_u32_e32 vcc, v4, v3
	s_nop 1
	v_cndmask_b32_e32 v0, v0, v5, vcc
	v_sub_u32_e32 v5, v4, v3
	v_cndmask_b32_e32 v4, v4, v5, vcc
	v_add_u32_e32 v5, 1, v0
	v_cmp_ge_u32_e32 vcc, v4, v3
	v_add_u32_e32 v4, 1, v6
	s_nop 0
	v_cndmask_b32_e32 v0, v0, v5, vcc
	v_mul_lo_u32 v5, v3, v0
	v_add_u32_e32 v3, v5, v3
	v_cmp_ne_u32_e32 vcc, v4, v3
	s_and_saveexec_b64 s[4:5], vcc
	s_xor_b64 s[4:5], exec, s[4:5]
	s_cbranch_execz .LBB0_1581
	s_waitcnt lgkmcnt(0)
	v_readlane_b32 s8, v253, 52
	v_readlane_b32 s9, v253, 53
	s_nop 4
	global_load_dword v2, v1, s[8:9] sc1
	s_waitcnt vmcnt(0)
	v_cmp_eq_u32_e32 vcc, v2, v0
	s_and_saveexec_b64 s[6:7], vcc
	s_cbranch_execz .LBB0_1580
	s_mov_b32 s20, 1
	s_mov_b64 s[10:11], 0
	s_branch .LBB0_1571

; __device__ __forceinline__ unsigned xb_ld(unsigned* p)              { return __hip_atomic_load(p, __ATOMIC_RELAXED, __HIP_MEMORY_SCOPE_AGENT); }
; __device__ __forceinline__ unsigned xb_add(unsigned* p, unsigned v) { return __hip_atomic_fetch_add(p, v, __ATOMIC_RELAXED, __HIP_MEMORY_SCOPE_AGENT); }
; #define XB_SPIN(cond, bar) do { unsigned _sp = 0; while (cond) { __builtin_amdgcn_s_sleep(1); \
;     if ((++_sp & 255u) == 0u) { if (xb_ld(&(bar)[XB_TMO])) break; if (_sp > XB_SPIN_CAP) { atomicAdd(&(bar)[XB_TMO], 1u); break; } } } } while (0)
; __device__ __forceinline__ void xcd_barrier(const XcdBarrier& b) {
;     ...
;             const unsigned tg = og / nx;
;             if (og + 1u == (tg + 1u) * nx) xb_add(&bar[XB_TOPGEN], 1u);
;             else XB_SPIN(xb_ld(&bar[XB_TOPGEN]) == tg, bar);
;             __builtin_amdgcn_fence(__ATOMIC_ACQUIRE, "agent");
;             xb_add(&bar[XB_XGEN(b.x)], 1u);
.LBB0_1599:
	s_bcnt1_i32_b64 s4, s[4:5]
	v_mov_b32_e32 v0, s4
	v_mov_b32_e32 v2, 0x2000
	s_getpc_b64 s[98:99]
